# v12 with the code between weight-prep(1) and the end of attention shifted by +32 bytes (placement), downstream pinned
# baseline (speedup 1.0000x reference)
; #define LAS __attribute__((address_space(3)))
; __device__ __forceinline__ void xcd_barrier(const XcdBarrier& b) {
;     asm volatile("s_waitcnt vmcnt(0)" ::: "memory");
; __global__ void __launch_bounds__(512, 2) fwd_kernel(Params p) {
;     ...
;         if (hs == 1) phase_wprep(p, 1, (LAS float*)lds);
;         xcd_barrier(xb);
.Lwpb_done:
	s_waitcnt vmcnt(0) lgkmcnt(0)
	.p2align 8
	s_nop 0
	s_nop 0
	s_nop 0
	s_nop 0
	s_nop 0
	s_nop 0
	s_nop 0
	s_nop 0
	s_nop 0
	s_nop 0
	s_nop 0
	s_nop 0
	s_nop 0
	s_nop 0
	s_nop 0
	s_nop 0
	s_nop 0
	s_nop 0
	s_nop 0
	s_nop 0
	s_nop 0
	s_nop 0
	s_nop 0
	s_nop 0
	s_nop 0
	s_nop 0
	s_nop 0
	s_nop 0
	s_nop 0
	s_nop 0
	s_nop 0
	s_nop 0
	s_nop 0
	s_nop 0
	s_nop 0
	s_nop 0
	s_nop 0
	s_nop 0
